# attention QK^T: each K-fragment LDS read issued right after the MFMA that frees its buffer (one MFMA earlier), waits adjusted
# baseline (speedup 1.0000x reference)
.LBB0_664:
	ds_read_b128 v[64:67], v220 offset:384
	ds_read_b128 v[68:71], v220 offset:256
	ds_read_b128 v[72:75], v220 offset:288
	ds_read_b128 v[100:103], v220 offset:416
	ds_read_b128 v[76:79], v220 offset:320
	ds_read_b128 v[104:107], v220 offset:448
	ds_read_b128 v[80:83], v220 offset:352
	ds_read_b128 v[108:111], v220 offset:480
	s_waitcnt lgkmcnt(5)
	v_sub_f32_e32 v91, v212, v75
	v_sub_f32_e32 v90, v212, v74
	v_sub_f32_e32 v89, v212, v73
	v_sub_f32_e32 v88, v212, v72
	v_sub_f32_e32 v87, v212, v71
	v_sub_f32_e32 v86, v212, v70
	v_sub_f32_e32 v85, v212, v69
	v_sub_f32_e32 v84, v212, v68
	s_waitcnt lgkmcnt(4)
	v_sub_f32_e32 v75, v212, v103
	v_sub_f32_e32 v74, v212, v102
	v_sub_f32_e32 v73, v212, v101
	v_sub_f32_e32 v72, v212, v100
	v_sub_f32_e32 v71, v212, v67
	v_sub_f32_e32 v70, v212, v66
	v_sub_f32_e32 v69, v212, v65
	v_sub_f32_e32 v68, v212, v64
	ds_read_b128 v[64:67], v214 offset:49152
	ds_read_b128 v[100:103], v214 offset:57344
	s_waitcnt lgkmcnt(3)
	v_sub_f32_e32 v99, v212, v83
	v_sub_f32_e32 v98, v212, v82
	v_sub_f32_e32 v97, v212, v81
	v_sub_f32_e32 v96, v212, v80
	v_sub_f32_e32 v95, v212, v79
	v_sub_f32_e32 v94, v212, v78
	v_sub_f32_e32 v93, v212, v77
	v_sub_f32_e32 v92, v212, v76
	s_waitcnt lgkmcnt(2)
	v_sub_f32_e32 v83, v212, v111
	v_sub_f32_e32 v82, v212, v110
	s_waitcnt lgkmcnt(1)
	v_mfma_f32_32x32x16_bf16 v[84:99], v[64:67], v[156:159], v[84:99]
	ds_read_b128 v[64:67], v213 offset:49152
	v_sub_f32_e32 v81, v212, v109
	v_sub_f32_e32 v80, v212, v108
	v_sub_f32_e32 v79, v212, v107
	v_sub_f32_e32 v78, v212, v106
	v_sub_f32_e32 v77, v212, v105
	v_sub_f32_e32 v76, v212, v104
	v_exp_f32_e32 v104, v160
	v_exp_f32_e32 v105, v161
	s_waitcnt lgkmcnt(1)
	v_mfma_f32_32x32x16_bf16 v[68:83], v[100:103], v[156:159], v[68:83]
	ds_read_b128 v[100:103], v213 offset:57344
	v_exp_f32_e32 v106, v126
	v_exp_f32_e32 v107, v127
	v_exp_f32_e32 v108, v122
	v_exp_f32_e32 v109, v123
	v_exp_f32_e32 v110, v120
	v_exp_f32_e32 v111, v121
	s_waitcnt lgkmcnt(1)
	v_mfma_f32_32x32x16_bf16 v[84:99], v[64:67], v[152:155], v[84:99]
	ds_read_b128 v[64:67], v211 offset:49152
	v_exp_f32_e32 v112, v116
	v_exp_f32_e32 v113, v117
	v_exp_f32_e32 v114, v162
	v_exp_f32_e32 v115, v163
	v_exp_f32_e32 v116, v124
	v_exp_f32_e32 v117, v125
	v_exp_f32_e32 v118, v118
	s_waitcnt lgkmcnt(1)
	v_mfma_f32_32x32x16_bf16 v[68:83], v[100:103], v[152:155], v[68:83]
	ds_read_b128 v[100:103], v211 offset:57344
	v_exp_f32_e32 v119, v119
	s_add_i32 s6, s46, 63
	s_waitcnt lgkmcnt(1)
	v_mfma_f32_32x32x16_bf16 v[84:99], v[64:67], v[148:151], v[84:99]
	ds_read_b128 v[64:67], v210 offset:49152
	s_waitcnt lgkmcnt(1)
	v_mfma_f32_32x32x16_bf16 v[68:83], v[100:103], v[148:151], v[68:83]
	ds_read_b128 v[100:103], v210 offset:57344
	s_waitcnt lgkmcnt(1)
	v_mfma_f32_32x32x16_bf16 v[84:99], v[64:67], v[144:147], v[84:99]
	ds_read_b128 v[64:67], v214 offset:49280
	s_waitcnt lgkmcnt(1)
	v_mfma_f32_32x32x16_bf16 v[68:83], v[100:103], v[144:147], v[68:83]
	ds_read_b128 v[100:103], v214 offset:57472
	s_waitcnt lgkmcnt(1)
	v_mfma_f32_32x32x16_bf16 v[84:99], v[64:67], v[140:143], v[84:99]
	ds_read_b128 v[64:67], v213 offset:49280
	s_waitcnt lgkmcnt(1)
	v_mfma_f32_32x32x16_bf16 v[68:83], v[100:103], v[140:143], v[68:83]
	ds_read_b128 v[100:103], v213 offset:57472
	s_waitcnt lgkmcnt(1)
	v_mfma_f32_32x32x16_bf16 v[84:99], v[64:67], v[136:139], v[84:99]
	ds_read_b128 v[64:67], v211 offset:49280
	s_waitcnt lgkmcnt(1)
	v_mfma_f32_32x32x16_bf16 v[68:83], v[100:103], v[136:139], v[68:83]
	ds_read_b128 v[100:103], v211 offset:57472
	s_waitcnt lgkmcnt(1)
	v_mfma_f32_32x32x16_bf16 v[84:99], v[64:67], v[132:135], v[84:99]
	ds_read_b128 v[64:67], v210 offset:49280
	s_waitcnt lgkmcnt(1)
	v_mfma_f32_32x32x16_bf16 v[68:83], v[100:103], v[132:135], v[68:83]
	ds_read_b128 v[100:103], v210 offset:57472
	s_waitcnt lgkmcnt(1)
	v_mfma_f32_32x32x16_bf16 v[84:99], v[64:67], v[128:131], v[84:99]
	v_add_f32_e32 v64, 0, v178
	v_add_f32_e32 v64, v180, v64
	v_add_f32_e32 v64, v175, v64
	v_add_f32_e32 v64, v179, v64
	v_add_f32_e32 v64, v174, v64
	v_add_f32_e32 v64, v177, v64
	v_add_f32_e32 v64, v172, v64
	v_add_f32_e32 v64, v173, v64
	v_add_f32_e32 v64, v169, v64
	v_add_f32_e32 v64, v171, v64
	v_add_f32_e32 v64, v167, v64
	v_add_f32_e32 v64, v170, v64
	v_add_f32_e32 v64, v165, v64
	v_add_f32_e32 v64, v168, v64
	v_add_f32_e32 v64, v164, v64
	v_add_f32_e32 v64, v166, v64
	v_add_f32_e32 v64, v104, v64
	v_add_f32_e32 v64, v105, v64
	v_add_f32_e32 v64, v106, v64
	v_add_f32_e32 v64, v107, v64
	v_add_f32_e32 v64, v108, v64
	v_add_f32_e32 v64, v109, v64
	v_add_f32_e32 v64, v110, v64
	v_add_f32_e32 v64, v111, v64
	v_add_f32_e32 v64, v112, v64
	v_add_f32_e32 v64, v113, v64
	s_waitcnt lgkmcnt(0)
	v_mfma_f32_32x32x16_bf16 v[68:83], v[100:103], v[128:131], v[68:83]
	v_add_f32_e32 v64, v114, v64
	v_add_f32_e32 v64, v115, v64
	v_add_f32_e32 v64, v116, v64
	v_add_f32_e32 v64, v117, v64
	v_add_f32_e32 v64, v118, v64
	v_add_f32_e32 v222, v119, v64
	v_mov_b32_e32 v223, v222
	s_nop 1
	v_permlane32_swap_b32_e32 v222, v223
	v_cvt_pk_bf16_f32 v64, v178, v180
	v_cvt_pk_bf16_f32 v65, v175, v179
	v_cvt_pk_bf16_f32 v66, v174, v177
	v_cvt_pk_bf16_f32 v67, v172, v173
	v_cvt_pk_bf16_f32 v100, v169, v171
	v_cvt_pk_bf16_f32 v101, v167, v170
	v_cvt_pk_bf16_f32 v102, v165, v168
	v_cvt_pk_bf16_f32 v103, v164, v166
	v_cvt_pk_bf16_f32 v104, v104, v105
	v_cvt_pk_bf16_f32 v105, v106, v107
	v_cvt_pk_bf16_f32 v106, v108, v109
	v_cvt_pk_bf16_f32 v107, v110, v111
	v_cvt_pk_bf16_f32 v108, v112, v113
	v_cvt_pk_bf16_f32 v109, v114, v115
	v_cvt_pk_bf16_f32 v110, v116, v117
	v_cvt_pk_bf16_f32 v111, v118, v119
	s_nop 0
	v_permlane32_swap_b32_e32 v64, v66
	v_permlane32_swap_b32_e32 v65, v67
	v_permlane32_swap_b32_e32 v100, v102
	v_permlane32_swap_b32_e32 v101, v103
	v_permlane32_swap_b32_e32 v104, v106
	v_permlane32_swap_b32_e32 v105, v107
	v_permlane32_swap_b32_e32 v108, v110
	v_permlane32_swap_b32_e32 v109, v111
	v_add_u32_e32 v226, s46, v193
	v_subrev_u32_e32 v112, 64, v226
	v_ashrrev_i32_e32 v113, 31, v112
	v_subrev_u32_e32 v116, 32, v226
	v_lshlrev_b64 v[112:113], 8, v[112:113]
	v_ashrrev_i32_e32 v117, 31, v116
	v_lshl_add_u64 v[114:115], v[194:195], 0, v[112:113]
	v_lshlrev_b64 v[116:117], 8, v[116:117]
	v_lshl_add_u64 v[112:113], v[196:197], 0, v[112:113]
	v_lshl_add_u64 v[118:119], v[194:195], 0, v[116:117]
	global_load_dwordx4 v[160:163], v[114:115], off
	global_load_dwordx4 v[164:167], v[118:119], off
	v_lshl_add_u64 v[114:115], v[196:197], 0, v[116:117]
	global_load_dwordx4 v[168:171], v[112:113], off
	global_load_dwordx4 v[172:175], v[114:115], off
	ds_read_b64_tr_b16 v[112:113], v203 offset:0
	ds_read_b64_tr_b16 v[114:115], v203 offset:0x800
	ds_read_b64_tr_b16 v[116:117], v203 offset:0x1000
	ds_read_b64_tr_b16 v[118:119], v203 offset:0x1800
	ds_read_b64_tr_b16 v[120:121], v203 offset:0x2000
	ds_read_b64_tr_b16 v[122:123], v203 offset:0x2800
	ds_read_b64_tr_b16 v[124:125], v203 offset:0x3000
	ds_read_b64_tr_b16 v[126:127], v203 offset:0x3800
	s_waitcnt lgkmcnt(0)
	s_nop 0
	v_mfma_f32_32x32x16_bf16 v[32:47], v[64:67], v[112:115], v[32:47]
	ds_read_b64_tr_b16 v[112:113], v203 offset:0x200
	ds_read_b64_tr_b16 v[114:115], v203 offset:0xa00
	v_mfma_f32_32x32x16_bf16 v[32:47], v[100:103], v[116:119], v[32:47]
	ds_read_b64_tr_b16 v[116:117], v203 offset:0x1200
	ds_read_b64_tr_b16 v[118:119], v203 offset:0x1a00
	v_mfma_f32_32x32x16_bf16 v[32:47], v[104:107], v[120:123], v[32:47]
	ds_read_b64_tr_b16 v[120:121], v203 offset:0x2200
	ds_read_b64_tr_b16 v[122:123], v203 offset:0x2a00
	v_mfma_f32_32x32x16_bf16 v[32:47], v[108:111], v[124:127], v[32:47]
	ds_read_b64_tr_b16 v[124:125], v203 offset:0x3200
	ds_read_b64_tr_b16 v[126:127], v203 offset:0x3a00
	s_waitcnt lgkmcnt(0)
	v_mfma_f32_32x32x16_bf16 v[48:63], v[64:67], v[112:115], v[48:63]
	ds_read_b64_tr_b16 v[112:113], v203 offset:0x400
	ds_read_b64_tr_b16 v[114:115], v203 offset:0xc00
	v_mfma_f32_32x32x16_bf16 v[48:63], v[100:103], v[116:119], v[48:63]
	ds_read_b64_tr_b16 v[116:117], v203 offset:0x1400
	ds_read_b64_tr_b16 v[118:119], v203 offset:0x1c00
	v_mfma_f32_32x32x16_bf16 v[48:63], v[104:107], v[120:123], v[48:63]
	ds_read_b64_tr_b16 v[120:121], v203 offset:0x2400
	ds_read_b64_tr_b16 v[122:123], v203 offset:0x2c00
	v_mfma_f32_32x32x16_bf16 v[48:63], v[108:111], v[124:127], v[48:63]
	ds_read_b64_tr_b16 v[124:125], v203 offset:0x3400
	ds_read_b64_tr_b16 v[126:127], v203 offset:0x3c00
	s_waitcnt lgkmcnt(0)
	v_mfma_f32_32x32x16_bf16 v[16:31], v[64:67], v[112:115], v[16:31]
	ds_read_b64_tr_b16 v[112:113], v203 offset:0x600
	ds_read_b64_tr_b16 v[114:115], v203 offset:0xe00
	v_mfma_f32_32x32x16_bf16 v[16:31], v[100:103], v[116:119], v[16:31]
	ds_read_b64_tr_b16 v[116:117], v203 offset:0x1600
	ds_read_b64_tr_b16 v[118:119], v203 offset:0x1e00
	v_mfma_f32_32x32x16_bf16 v[16:31], v[104:107], v[120:123], v[16:31]
	ds_read_b64_tr_b16 v[120:121], v203 offset:0x2600
	ds_read_b64_tr_b16 v[122:123], v203 offset:0x2e00
	v_mfma_f32_32x32x16_bf16 v[16:31], v[108:111], v[124:127], v[16:31]
	ds_read_b64_tr_b16 v[124:125], v203 offset:0x3600
	ds_read_b64_tr_b16 v[126:127], v203 offset:0x3e00
	s_waitcnt lgkmcnt(0)
	v_mfma_f32_32x32x16_bf16 v[0:15], v[64:67], v[112:115], v[0:15]
	s_cmp_le_i32 s6, s31
	s_cselect_b64 s[6:7], -1, 0
	s_cmp_gt_i32 s46, s47
	s_cselect_b64 s[34:35], -1, 0
	s_and_b64 s[6:7], s[6:7], s[34:35]
	s_and_b64 vcc, exec, s[6:7]
	v_mfma_f32_32x32x16_bf16 v[0:15], v[100:103], v[116:119], v[0:15]
	v_mfma_f32_32x32x16_bf16 v[0:15], v[104:107], v[120:123], v[0:15]
	v_mfma_f32_32x32x16_bf16 v[0:15], v[108:111], v[124:127], v[0:15]
	s_cbranch_vccnz .LBB0_666
	v_subrev_u32_e32 v64, 64, v221
	v_cmp_gt_u32_e32 vcc, s93, v64
	v_add_u32_e32 v64, 0xfffff7a0, v221
	s_nop 0
	v_cndmask_b32_e32 v84, v251, v84, vcc
	v_cmp_lt_u32_e32 vcc, s26, v64
	v_add_u32_e32 v64, 0xfffff7bf, v221
	s_nop 0
	v_cndmask_b32_e32 v68, v251, v68, vcc
	v_cmp_lt_u32_e32 vcc, s26, v64
	v_add_u32_e32 v64, 0xfffff79f, v221
	s_nop 0
	v_cndmask_b32_e32 v85, v251, v85, vcc
	v_cmp_lt_u32_e32 vcc, s26, v64
	v_add_u32_e32 v64, 0xfffff7be, v221
	s_nop 0
	v_cndmask_b32_e32 v69, v251, v69, vcc
	v_cmp_lt_u32_e32 vcc, s26, v64
	v_add_u32_e32 v64, 0xfffff79e, v221
	s_nop 0
	v_cndmask_b32_e32 v86, v251, v86, vcc
	v_cmp_lt_u32_e32 vcc, s26, v64
	v_add_u32_e32 v64, 0xfffff7bd, v221
	s_nop 0
	v_cndmask_b32_e32 v70, v251, v70, vcc
	v_cmp_lt_u32_e32 vcc, s26, v64
	v_add_u32_e32 v64, 0xfffff79d, v221
	s_nop 0
	v_cndmask_b32_e32 v87, v251, v87, vcc
	v_cmp_lt_u32_e32 vcc, s26, v64
	v_add_u32_e32 v64, 0xfffff7b8, v221
	s_nop 0
	v_cndmask_b32_e32 v71, v251, v71, vcc
	v_cmp_lt_u32_e32 vcc, s26, v64
	v_add_u32_e32 v64, 0xfffff798, v221
	s_nop 0
	v_cndmask_b32_e32 v88, v251, v88, vcc
	v_cmp_lt_u32_e32 vcc, s26, v64
	v_add_u32_e32 v64, 0xfffff7b7, v221
	s_nop 0
	v_cndmask_b32_e32 v72, v251, v72, vcc
	v_cmp_lt_u32_e32 vcc, s26, v64
	v_add_u32_e32 v64, 0xfffff797, v221
	s_nop 0
	v_cndmask_b32_e32 v89, v251, v89, vcc
	v_cmp_lt_u32_e32 vcc, s26, v64
	v_add_u32_e32 v64, 0xfffff7b6, v221
	s_nop 0
	v_cndmask_b32_e32 v73, v251, v73, vcc
	v_cmp_lt_u32_e32 vcc, s26, v64
	v_add_u32_e32 v64, 0xfffff796, v221
	s_nop 0
	v_cndmask_b32_e32 v90, v251, v90, vcc
	v_cmp_lt_u32_e32 vcc, s26, v64
	v_add_u32_e32 v64, 0xfffff7b5, v221
	s_nop 0
	v_cndmask_b32_e32 v74, v251, v74, vcc
	v_cmp_lt_u32_e32 vcc, s26, v64
	v_add_u32_e32 v64, 0xfffff795, v221
	s_nop 0
	v_cndmask_b32_e32 v91, v251, v91, vcc
	v_cmp_lt_u32_e32 vcc, s26, v64
	v_add_u32_e32 v64, 0xfffff7b0, v221
	s_nop 0
	v_cndmask_b32_e32 v75, v251, v75, vcc
	v_cmp_lt_u32_e32 vcc, s26, v64
	v_add_u32_e32 v64, 0xfffff790, v221
	s_nop 0
	v_cndmask_b32_e32 v92, v251, v92, vcc
	v_cmp_lt_u32_e32 vcc, s26, v64
	v_add_u32_e32 v64, 0xfffff7af, v221
	s_nop 0
	v_cndmask_b32_e32 v76, v251, v76, vcc
	v_cmp_lt_u32_e32 vcc, s26, v64
	v_add_u32_e32 v64, 0xfffff78f, v221
	s_nop 0
	v_cndmask_b32_e32 v93, v251, v93, vcc
	v_cmp_lt_u32_e32 vcc, s26, v64
	v_add_u32_e32 v64, 0xfffff7ae, v221
	s_nop 0
	v_cndmask_b32_e32 v77, v251, v77, vcc
	v_cmp_lt_u32_e32 vcc, s26, v64
	v_add_u32_e32 v64, 0xfffff78e, v221
	s_nop 0
	v_cndmask_b32_e32 v94, v251, v94, vcc
	v_cmp_lt_u32_e32 vcc, s26, v64
	v_add_u32_e32 v64, 0xfffff7ad, v221
	s_nop 0
	v_cndmask_b32_e32 v78, v251, v78, vcc
	v_cmp_lt_u32_e32 vcc, s26, v64
	v_add_u32_e32 v64, 0xfffff78d, v221
	s_nop 0
	v_cndmask_b32_e32 v95, v251, v95, vcc
	v_cmp_lt_u32_e32 vcc, s26, v64
	v_add_u32_e32 v64, 0xfffff7a8, v221
	s_nop 0
	v_cndmask_b32_e32 v79, v251, v79, vcc
	v_cmp_lt_u32_e32 vcc, s26, v64
	v_add_u32_e32 v64, 0xfffff788, v221
	s_nop 0
	v_cndmask_b32_e32 v96, v251, v96, vcc
	v_cmp_lt_u32_e32 vcc, s26, v64
	v_add_u32_e32 v64, 0xfffff7a7, v221
	s_nop 0
	v_cndmask_b32_e32 v80, v251, v80, vcc
	v_cmp_lt_u32_e32 vcc, s26, v64
	v_add_u32_e32 v64, 0xfffff787, v221
	s_nop 0
	v_cndmask_b32_e32 v97, v251, v97, vcc
	v_cmp_lt_u32_e32 vcc, s26, v64
	v_add_u32_e32 v64, 0xfffff7a6, v221
	s_nop 0
	v_cndmask_b32_e32 v81, v251, v81, vcc
	v_cmp_lt_u32_e32 vcc, s26, v64
	v_add_u32_e32 v64, 0xfffff786, v221
	s_nop 0
	v_cndmask_b32_e32 v98, v251, v98, vcc
	v_cmp_lt_u32_e32 vcc, s26, v64
	v_add_u32_e32 v64, 0xfffff7a5, v221
	s_nop 0
	v_cndmask_b32_e32 v82, v251, v82, vcc
	v_cmp_lt_u32_e32 vcc, s26, v64
	v_add_u32_e32 v64, 0xfffff785, v221
	s_nop 0
	v_cndmask_b32_e32 v99, v251, v99, vcc
	v_cmp_lt_u32_e32 vcc, s26, v64
	s_nop 1
	v_cndmask_b32_e32 v83, v251, v83, vcc

.LBB0_670:
	v_cndmask_b32_e64 v225, v64, v176, s[6:7]
	v_mul_f32_e32 v176, 0xbe0293ee, v225
	v_fmamk_f32 v64, v84, 0x3e0293ee, v176
	v_fmamk_f32 v65, v85, 0x3e0293ee, v176
	v_fmamk_f32 v66, v86, 0x3e0293ee, v176
	v_fmamk_f32 v67, v87, 0x3e0293ee, v176
	v_fmamk_f32 v100, v88, 0x3e0293ee, v176
	v_fmamk_f32 v101, v89, 0x3e0293ee, v176
	v_fmamk_f32 v102, v90, 0x3e0293ee, v176
	v_fmamk_f32 v103, v91, 0x3e0293ee, v176
	v_fmamk_f32 v104, v92, 0x3e0293ee, v176
	v_fmamk_f32 v105, v93, 0x3e0293ee, v176
	v_fmamk_f32 v106, v94, 0x3e0293ee, v176
	v_fmamk_f32 v107, v95, 0x3e0293ee, v176
	v_fmamk_f32 v96, v96, 0x3e0293ee, v176
	v_fmamk_f32 v97, v97, 0x3e0293ee, v176
	v_fmamk_f32 v98, v98, 0x3e0293ee, v176
	v_fmamk_f32 v99, v99, 0x3e0293ee, v176
	v_fmamk_f32 v84, v68, 0x3e0293ee, v176
	v_fmamk_f32 v85, v69, 0x3e0293ee, v176
	v_fmamk_f32 v93, v70, 0x3e0293ee, v176
	v_fmamk_f32 v94, v71, 0x3e0293ee, v176
	v_fmamk_f32 v95, v72, 0x3e0293ee, v176
	v_fmamk_f32 v177, v73, 0x3e0293ee, v176
	v_fmamk_f32 v86, v74, 0x3e0293ee, v176
	v_fmamk_f32 v87, v75, 0x3e0293ee, v176
	v_fmamk_f32 v88, v76, 0x3e0293ee, v176
	v_fmamk_f32 v89, v77, 0x3e0293ee, v176
	v_fmamk_f32 v90, v78, 0x3e0293ee, v176
	v_fmamk_f32 v91, v79, 0x3e0293ee, v176
	v_exp_f32_e32 v64, v64
	v_exp_f32_e32 v65, v65
	v_exp_f32_e32 v66, v66
	v_exp_f32_e32 v67, v67
	v_exp_f32_e32 v68, v100
	v_exp_f32_e32 v69, v101
	v_exp_f32_e32 v70, v102
	v_exp_f32_e32 v71, v103
	v_exp_f32_e32 v72, v104
	v_exp_f32_e32 v73, v105
	v_exp_f32_e32 v74, v106
	v_exp_f32_e32 v75, v107
	v_exp_f32_e32 v76, v96
	v_exp_f32_e32 v77, v97
	v_exp_f32_e32 v78, v98
	v_exp_f32_e32 v79, v99
	v_fmamk_f32 v92, v80, 0x3e0293ee, v176
	v_fmamk_f32 v178, v81, 0x3e0293ee, v176
	v_fmamk_f32 v179, v82, 0x3e0293ee, v176
	v_fmac_f32_e32 v176, 0x3e0293ee, v83
	s_waitcnt lgkmcnt(0)
	s_barrier
	ds_read_b128 v[80:83], v220 offset:128
	ds_read_b128 v[96:99], v220
	ds_read_b128 v[100:103], v220 offset:32
	ds_read_b128 v[180:183], v220 offset:160
	ds_read_b128 v[104:107], v220 offset:64
	ds_read_b128 v[184:187], v220 offset:192
	ds_read_b128 v[108:111], v220 offset:96
	ds_read_b128 v[188:191], v220 offset:224
	s_waitcnt lgkmcnt(5)
	v_sub_f32_e32 v119, v212, v103
	v_sub_f32_e32 v118, v212, v102
	v_sub_f32_e32 v117, v212, v101
	v_sub_f32_e32 v116, v212, v100
	v_sub_f32_e32 v115, v212, v99
	v_sub_f32_e32 v114, v212, v98
	v_sub_f32_e32 v113, v212, v97
	v_sub_f32_e32 v112, v212, v96
	s_waitcnt lgkmcnt(4)
	v_sub_f32_e32 v103, v212, v183
	v_sub_f32_e32 v102, v212, v182
	v_sub_f32_e32 v101, v212, v181
	v_sub_f32_e32 v100, v212, v180
	v_sub_f32_e32 v99, v212, v83
	v_sub_f32_e32 v98, v212, v82
	v_sub_f32_e32 v97, v212, v81
	v_sub_f32_e32 v96, v212, v80
	ds_read_b128 v[80:83], v214 offset:32768
	ds_read_b128 v[180:183], v214 offset:40960
	s_waitcnt lgkmcnt(3)
	v_sub_f32_e32 v127, v212, v111
	v_sub_f32_e32 v126, v212, v110
	v_sub_f32_e32 v125, v212, v109
	v_sub_f32_e32 v124, v212, v108
	v_sub_f32_e32 v123, v212, v107
	v_sub_f32_e32 v122, v212, v106
	v_sub_f32_e32 v121, v212, v105
	v_sub_f32_e32 v120, v212, v104
	s_waitcnt lgkmcnt(2)
	v_sub_f32_e32 v111, v212, v191
	v_sub_f32_e32 v110, v212, v190
	s_waitcnt lgkmcnt(1)
	v_mfma_f32_32x32x16_bf16 v[112:127], v[80:83], v[156:159], v[112:127]
	ds_read_b128 v[80:83], v213 offset:32768
	v_sub_f32_e32 v109, v212, v189
	v_sub_f32_e32 v108, v212, v188
	v_sub_f32_e32 v107, v212, v187
	v_sub_f32_e32 v106, v212, v186
	v_sub_f32_e32 v105, v212, v185
	v_sub_f32_e32 v104, v212, v184
	v_exp_f32_e32 v86, v86
	v_exp_f32_e32 v87, v87
	s_waitcnt lgkmcnt(1)
	v_mfma_f32_32x32x16_bf16 v[96:111], v[180:183], v[156:159], v[96:111]
	ds_read_b128 v[180:183], v213 offset:40960
	v_exp_f32_e32 v88, v88
	v_exp_f32_e32 v89, v89
	v_exp_f32_e32 v90, v90
	v_exp_f32_e32 v91, v91
	v_exp_f32_e32 v92, v92
	s_waitcnt lgkmcnt(1)
	v_mfma_f32_32x32x16_bf16 v[112:127], v[80:83], v[152:155], v[112:127]
	ds_read_b128 v[80:83], v211 offset:32768
	s_waitcnt lgkmcnt(1)
	v_mfma_f32_32x32x16_bf16 v[96:111], v[180:183], v[152:155], v[96:111]
	ds_read_b128 v[180:183], v211 offset:40960
	s_waitcnt lgkmcnt(1)
	v_mfma_f32_32x32x16_bf16 v[112:127], v[80:83], v[148:151], v[112:127]
	ds_read_b128 v[80:83], v210 offset:32768
	s_waitcnt lgkmcnt(1)
	v_mfma_f32_32x32x16_bf16 v[96:111], v[180:183], v[148:151], v[96:111]
	ds_read_b128 v[180:183], v210 offset:40960
	s_waitcnt lgkmcnt(1)
	v_mfma_f32_32x32x16_bf16 v[112:127], v[80:83], v[144:147], v[112:127]
	ds_read_b128 v[80:83], v214 offset:32896
	s_waitcnt lgkmcnt(1)
	v_mfma_f32_32x32x16_bf16 v[96:111], v[180:183], v[144:147], v[96:111]
	ds_read_b128 v[180:183], v214 offset:41088
	s_waitcnt lgkmcnt(1)
	v_mfma_f32_32x32x16_bf16 v[112:127], v[80:83], v[140:143], v[112:127]
	ds_read_b128 v[80:83], v213 offset:32896
	s_waitcnt lgkmcnt(1)
	v_mfma_f32_32x32x16_bf16 v[96:111], v[180:183], v[140:143], v[96:111]
	ds_read_b128 v[180:183], v213 offset:41088
	s_waitcnt lgkmcnt(1)
	v_mfma_f32_32x32x16_bf16 v[112:127], v[80:83], v[136:139], v[112:127]
	ds_read_b128 v[80:83], v211 offset:32896
	s_waitcnt lgkmcnt(1)
	v_mfma_f32_32x32x16_bf16 v[96:111], v[180:183], v[136:139], v[96:111]
	ds_read_b128 v[180:183], v211 offset:41088
	s_waitcnt lgkmcnt(1)
	v_mfma_f32_32x32x16_bf16 v[112:127], v[80:83], v[132:135], v[112:127]
	ds_read_b128 v[80:83], v210 offset:32896
	s_waitcnt lgkmcnt(1)
	v_mfma_f32_32x32x16_bf16 v[96:111], v[180:183], v[132:135], v[96:111]
	ds_read_b128 v[180:183], v210 offset:41088
	s_waitcnt lgkmcnt(1)
	v_mfma_f32_32x32x16_bf16 v[112:127], v[80:83], v[128:131], v[112:127]
	v_exp_f32_e32 v80, v84
	v_exp_f32_e32 v84, v95
	v_exp_f32_e32 v95, v176
	v_add_f32_e32 v176, 0, v64
	v_add_f32_e32 v176, v65, v176
	v_add_f32_e32 v176, v66, v176
	v_add_f32_e32 v176, v67, v176
	v_add_f32_e32 v176, v68, v176
	v_add_f32_e32 v176, v69, v176
	v_add_f32_e32 v176, v70, v176
	v_add_f32_e32 v176, v71, v176
	v_add_f32_e32 v176, v72, v176
	v_add_f32_e32 v176, v73, v176
	v_add_f32_e32 v176, v74, v176
	v_add_f32_e32 v176, v75, v176
	v_add_f32_e32 v176, v76, v176
	v_exp_f32_e32 v81, v85
	v_add_f32_e32 v176, v77, v176
	v_exp_f32_e32 v82, v93
	v_add_f32_e32 v176, v78, v176
	v_exp_f32_e32 v83, v94
	v_add_f32_e32 v176, v79, v176
	v_add_f32_e32 v176, v80, v176
	v_exp_f32_e32 v85, v177
	v_add_f32_e32 v176, v81, v176
	v_add_f32_e32 v176, v82, v176
	v_add_f32_e32 v176, v83, v176
	v_add_f32_e32 v176, v84, v176
	v_add_f32_e32 v176, v85, v176
	v_add_f32_e32 v176, v86, v176
	v_add_f32_e32 v176, v87, v176
	v_add_f32_e32 v176, v88, v176
	v_exp_f32_e32 v93, v178
	v_add_f32_e32 v176, v89, v176
	s_waitcnt lgkmcnt(0)
	v_mfma_f32_32x32x16_bf16 v[96:111], v[180:183], v[128:131], v[96:111]
	v_exp_f32_e32 v94, v179
	v_add_f32_e32 v176, v90, v176
	v_add_f32_e32 v176, v91, v176
	v_add_f32_e32 v176, v92, v176
	v_add_f32_e32 v176, v93, v176
	v_add_f32_e32 v176, v94, v176
	v_add_f32_e32 v227, v95, v176
	v_mov_b32_e32 v228, v227
	v_cvt_pk_bf16_f32 v176, v64, v65
	v_cvt_pk_bf16_f32 v177, v66, v67
	v_cvt_pk_bf16_f32 v178, v68, v69
	v_cvt_pk_bf16_f32 v179, v70, v71
	v_cvt_pk_bf16_f32 v180, v72, v73
	v_cvt_pk_bf16_f32 v181, v74, v75
	v_cvt_pk_bf16_f32 v182, v76, v77
	v_cvt_pk_bf16_f32 v183, v78, v79
	v_cvt_pk_bf16_f32 v188, v80, v81
	v_cvt_pk_bf16_f32 v189, v82, v83
	v_cvt_pk_bf16_f32 v190, v84, v85
	v_cvt_pk_bf16_f32 v191, v86, v87
	v_cvt_pk_bf16_f32 v184, v88, v89
	v_cvt_pk_bf16_f32 v185, v90, v91
	v_cvt_pk_bf16_f32 v186, v92, v93
	v_cvt_pk_bf16_f32 v187, v94, v95
	s_nop 1
	v_permlane32_swap_b32_e32 v227, v228
	v_permlane32_swap_b32_e32 v176, v178
	v_permlane32_swap_b32_e32 v177, v179
	v_permlane32_swap_b32_e32 v180, v182
	v_permlane32_swap_b32_e32 v181, v183
	v_permlane32_swap_b32_e32 v188, v190
	v_permlane32_swap_b32_e32 v189, v191
	v_permlane32_swap_b32_e32 v184, v186
	v_permlane32_swap_b32_e32 v185, v187
	s_add_i32 s6, s48, 1
	s_cmp_lt_u32 s6, s45
	s_cselect_b64 s[34:35], -1, 0
	s_cmp_ge_u32 s6, s45
	s_cbranch_scc1 .LBB0_672
	v_add_u32_e32 v160, 0xffffff80, v226
	v_add_u32_e32 v162, 0xffffffa0, v226
	v_ashrrev_i32_e32 v161, 31, v160
	v_ashrrev_i32_e32 v163, 31, v162
	v_lshlrev_b64 v[168:169], 8, v[160:161]
	v_lshlrev_b64 v[170:171], 8, v[162:163]
	v_lshl_add_u64 v[160:161], v[194:195], 0, v[168:169]
	v_lshl_add_u64 v[164:165], v[194:195], 0, v[170:171]
	v_lshl_add_u64 v[168:169], v[196:197], 0, v[168:169]
	v_lshl_add_u64 v[172:173], v[196:197], 0, v[170:171]
	global_load_dwordx4 v[160:163], v[160:161], off
	s_nop 0
	global_load_dwordx4 v[164:167], v[164:165], off
	s_nop 0
	global_load_dwordx4 v[168:171], v[168:169], off
	s_nop 0
	global_load_dwordx4 v[172:175], v[172:173], off
